# phase 0 w_in transpose: all loads of a thread's grid-stride iterations issued before the first wait (on top of the balanced phase 0)
# speedup vs baseline: 1.0061x; 1.0061x over previous
; DI unsigned cvtpk(float lo, float hi) { f32x2 v = {lo, hi}; bf16x2_t b = __builtin_convertvector(v, bf16x2_t); return __builtin_bit_cast(unsigned, b); }
; DI void xpose_cvt(const float* __restrict__ src, bf16_t* __restrict__ dst, int K, int N, int Npad, bool perm_kv, size_t gtid, size_t gstride) {
;   const size_t total = (size_t)Npad * (K >> 3);
; #pragma nounroll
;   for (size_t i = gtid; i < total; i += gstride) {
;     const int n = (int)(i % Npad), kb = (int)(i / Npad);
;     float v[8];
; #pragma unroll
;     for (int e = 0; e < 8; ++e) v[e] = (n < N) ? src[(size_t)(8 * kb + e) * N + n] : 0.f;
;     int row = n;
;     if (perm_kv) { const int hh = n >> 7, wv = n & 127; row = (wv < 64) ? (64 * hh + wv) : (256 + 64 * hh + (wv - 64)); }
;     u32x4 o = {cvtpk(v[0], v[1]), cvtpk(v[2], v[3]), cvtpk(v[4], v[5]), cvtpk(v[6], v[7])};
;     *(u32x4*)(dst + (size_t)row * K + 8 * kb) = o;
;   }
; DI void phase0(KP p, char* lds) {
;     ...
;     xpose_cvt(p->w_in + (size_t)l * 1024 * NIN, (bf16_t*)(ws + WS_WIN) + (size_t)l * NINP * 1024, 1024, NIN, NINP, false, gtid, gstride);
.LBB0_367:
	s_and_saveexec_b64 s[52:53], s[42:43]
	s_cbranch_execz .LBB0_386
	s_mul_i32 s18, s76, 0xa60000
	s_add_u32 s64, s4, s18
	s_addc_u32 s65, s5, 0
	s_mul_i32 s18, s76, 0x580000
	s_add_u32 s18, s2, s18
	s_addc_u32 s19, s69, 0
	s_mov_b64 s[20:21], 0
	s_mov_b64 s[20:21], exec
	s_mov_b32 s34, 0xba2e8ba3
	v_mov_b32_e32 v63, 0
	v_mul_hi_u32 v91, v4, s34
	v_lshrrev_b32_e32 v91, 11, v91
	v_mul_u32_u24_e32 v61, 0xb00, v91
	v_sub_u32_e32 v88, v4, v61
	v_mul_u32_u24_e32 v61, 0x5300, v91
	v_add_lshl_u32 v58, v61, v88, 2
	v_lshlrev_b32_e32 v62, 11, v88
	v_lshl_add_u32 v62, v91, 4, v62
	v_lshl_add_u64 v[82:83], s[18:19], 0, v[62:63]
	v_mov_b32_e32 v34, 0
	v_mov_b32_e32 v35, 0
	v_mov_b32_e32 v36, 0
	v_mov_b32_e32 v37, 0
	v_mov_b32_e32 v38, 0
	v_mov_b32_e32 v39, 0
	v_mov_b32_e32 v40, 0
	v_mov_b32_e32 v41, 0
	v_add_u32_e32 v64, 0x20000, v4
	v_mul_hi_u32 v92, v64, s34
	v_lshrrev_b32_e32 v92, 11, v92
	v_mul_u32_u24_e32 v61, 0xb00, v92
	v_sub_u32_e32 v89, v64, v61
	v_mul_u32_u24_e32 v61, 0x5300, v92
	v_add_lshl_u32 v59, v61, v89, 2
	v_lshlrev_b32_e32 v62, 11, v89
	v_lshl_add_u32 v62, v92, 4, v62
	v_lshl_add_u64 v[84:85], s[18:19], 0, v[62:63]
	v_mov_b32_e32 v42, 0
	v_mov_b32_e32 v43, 0
	v_mov_b32_e32 v44, 0
	v_mov_b32_e32 v45, 0
	v_mov_b32_e32 v46, 0
	v_mov_b32_e32 v47, 0
	v_mov_b32_e32 v48, 0
	v_mov_b32_e32 v49, 0
	v_add_u32_e32 v64, 0x40000, v4
	v_mul_hi_u32 v93, v64, s34
	v_lshrrev_b32_e32 v93, 11, v93
	v_mul_u32_u24_e32 v61, 0xb00, v93
	v_sub_u32_e32 v90, v64, v61
	v_mul_u32_u24_e32 v61, 0x5300, v93
	v_add_lshl_u32 v60, v61, v90, 2
	v_lshlrev_b32_e32 v62, 11, v90
	v_lshl_add_u32 v62, v93, 4, v62
	v_lshl_add_u64 v[86:87], s[18:19], 0, v[62:63]
	v_mov_b32_e32 v50, 0
	v_mov_b32_e32 v51, 0
	v_mov_b32_e32 v52, 0
	v_mov_b32_e32 v53, 0
	v_mov_b32_e32 v54, 0
	v_mov_b32_e32 v55, 0
	v_mov_b32_e32 v56, 0
	v_mov_b32_e32 v57, 0
	v_cmp_gt_u32_e32 vcc, 0x18000, v4
	s_nop 3
	s_mov_b64 s[34:35], vcc
	s_waitcnt vmcnt(0)
	v_cmp_gt_u32_e32 vcc, s60, v88
	s_nop 3
	s_and_b64 exec, s[20:21], vcc
	global_load_dword v34, v58, s[64:65]
	s_add_u32 s50, s64, 0x2980
	s_addc_u32 s51, s65, 0
	global_load_dword v35, v58, s[50:51]
	s_add_u32 s50, s64, 0x5300
	s_addc_u32 s51, s65, 0
	global_load_dword v36, v58, s[50:51]
	s_add_u32 s50, s64, 0x7c80
	s_addc_u32 s51, s65, 0
	global_load_dword v37, v58, s[50:51]
	s_add_u32 s50, s64, 0xa600
	s_addc_u32 s51, s65, 0
	global_load_dword v38, v58, s[50:51]
	s_add_u32 s50, s64, 0xcf80
	s_addc_u32 s51, s65, 0
	global_load_dword v39, v58, s[50:51]
	s_add_u32 s50, s64, 0xf900
	s_addc_u32 s51, s65, 0
	global_load_dword v40, v58, s[50:51]
	s_add_u32 s50, s64, 0x12280
	s_addc_u32 s51, s65, 0
	global_load_dword v41, v58, s[50:51]
	s_mov_b64 exec, s[20:21]
	v_cmp_gt_u32_e32 vcc, s60, v89
	s_nop 3
	s_and_b64 exec, s[20:21], vcc
	global_load_dword v42, v59, s[64:65]
	s_add_u32 s50, s64, 0x2980
	s_addc_u32 s51, s65, 0
	global_load_dword v43, v59, s[50:51]
	s_add_u32 s50, s64, 0x5300
	s_addc_u32 s51, s65, 0
	global_load_dword v44, v59, s[50:51]
	s_add_u32 s50, s64, 0x7c80
	s_addc_u32 s51, s65, 0
	global_load_dword v45, v59, s[50:51]
	s_add_u32 s50, s64, 0xa600
	s_addc_u32 s51, s65, 0
	global_load_dword v46, v59, s[50:51]
	s_add_u32 s50, s64, 0xcf80
	s_addc_u32 s51, s65, 0
	global_load_dword v47, v59, s[50:51]
	s_add_u32 s50, s64, 0xf900
	s_addc_u32 s51, s65, 0
	global_load_dword v48, v59, s[50:51]
	s_add_u32 s50, s64, 0x12280
	s_addc_u32 s51, s65, 0
	global_load_dword v49, v59, s[50:51]
	s_mov_b64 exec, s[20:21]
	v_cmp_gt_u32_e32 vcc, s60, v90
	s_nop 3
	s_and_b64 vcc, vcc, s[34:35]
	s_and_b64 exec, s[20:21], vcc
	global_load_dword v50, v60, s[64:65]
	s_add_u32 s50, s64, 0x2980
	s_addc_u32 s51, s65, 0
	global_load_dword v51, v60, s[50:51]
	s_add_u32 s50, s64, 0x5300
	s_addc_u32 s51, s65, 0
	global_load_dword v52, v60, s[50:51]
	s_add_u32 s50, s64, 0x7c80
	s_addc_u32 s51, s65, 0
	global_load_dword v53, v60, s[50:51]
	s_add_u32 s50, s64, 0xa600
	s_addc_u32 s51, s65, 0
	global_load_dword v54, v60, s[50:51]
	s_add_u32 s50, s64, 0xcf80
	s_addc_u32 s51, s65, 0
	global_load_dword v55, v60, s[50:51]
	s_add_u32 s50, s64, 0xf900
	s_addc_u32 s51, s65, 0
	global_load_dword v56, v60, s[50:51]
	s_add_u32 s50, s64, 0x12280
	s_addc_u32 s51, s65, 0
	global_load_dword v57, v60, s[50:51]
	s_mov_b64 exec, s[20:21]
	s_waitcnt vmcnt(16)
	v_cvt_pk_bf16_f32 v94, v34, v35
	v_cvt_pk_bf16_f32 v95, v36, v37
	v_cvt_pk_bf16_f32 v96, v38, v39
	v_cvt_pk_bf16_f32 v97, v40, v41
	s_waitcnt vmcnt(8)
	v_cvt_pk_bf16_f32 v98, v42, v43
	v_cvt_pk_bf16_f32 v99, v44, v45
	v_cvt_pk_bf16_f32 v100, v46, v47
	v_cvt_pk_bf16_f32 v101, v48, v49
	s_waitcnt vmcnt(0)
	v_cvt_pk_bf16_f32 v102, v50, v51
	v_cvt_pk_bf16_f32 v103, v52, v53
	v_cvt_pk_bf16_f32 v104, v54, v55
	v_cvt_pk_bf16_f32 v105, v56, v57
	global_store_dwordx4 v[82:83], v[94:97], off
	global_store_dwordx4 v[84:85], v[98:101], off
	s_and_b64 exec, s[20:21], s[34:35]
	global_store_dwordx4 v[86:87], v[102:105], off
	s_mov_b64 exec, s[20:21]
